# P3 alpha: KA/V/EV stage loads issued as soon as their address is ready (before the decay-scale chain), vmcnt waits recomputed
# speedup vs baseline: 1.0293x; 1.0015x over previous
.LBB0_350:
	s_add_i32 s34, s47, 1
	s_and_b64 s[20:21], exec, s[38:39]
	s_cselect_b32 s48, s44, s34
	s_waitcnt vmcnt(18)
	ds_write_b128 v168, v[32:35] offset:44032
	s_waitcnt vmcnt(16)
	ds_write_b128 v168, v[36:39] offset:52736
	s_waitcnt vmcnt(15)
	ds_write_b128 v168, v[40:43] offset:61440
	s_waitcnt vmcnt(13)
	ds_write_b128 v166, v[44:47] offset:8704
	s_waitcnt vmcnt(17)
	ds_write_b128 v167, v[48:51]
	v_add_u32_e32 v32, s61, v138
	s_min_u32 s49, s44, 60
	s_waitcnt vmcnt(14)
	s_cmp_lg_u32 s69, 0
	s_cbranch_scc1 .Lev_skip_a
	ds_write_b128 v32, v[52:55]
.Lev_skip_a:
	s_add_i32 s34, s49, 3
	v_sub_u32_e64 v32, 60, s44 clamp
	s_and_b64 s[20:21], exec, s[38:39]
	v_readfirstlane_b32 s20, v32
	s_cselect_b32 s66, s34, s20
	s_lshl_b32 s34, s66, 13
	s_lshl_b32 s67, s66, 14
	s_add_u32 s20, s43, s67
	s_addc_u32 s21, s63, 0
	v_lshl_add_u64 v[36:37], s[20:21], 0, v[120:121]
	global_load_dwordx4 v[32:35], v120, s[20:21] nt
	v_add_co_u32_e64 v36, s[20:21], s60, v36
	v_lshl_add_u64 v[48:49], v[146:147], 0, s[34:35]
	global_load_dwordx4 v[48:51], v[48:49], off nt
	s_nop 0
	v_addc_co_u32_e64 v37, s[20:21], 0, v37, s[20:21]
	s_add_u32 s20, s64, s67
	s_addc_u32 s21, s65, 0
	v_lshl_add_u64 v[44:45], s[20:21], 0, v[120:121]
	global_load_dwordx4 v[36:39], v[36:37], off nt
	s_lshl_b32 s34, s66, 10
	global_load_dwordx4 v[40:43], v120, s[20:21] nt
	v_add_co_u32_e64 v44, s[20:21], s60, v44
	v_lshl_add_u64 v[52:53], v[148:149], 0, s[34:35]
	global_load_dwordx4 v[52:55], v[52:53], off
	s_nop 0
	v_addc_co_u32_e64 v45, s[20:21], 0, v45, s[20:21]
	global_load_dwordx4 v[44:47], v[44:45], off nt
	s_lshl_b32 s20, s49, 1
	s_add_i32 s34, s20, 4
	s_waitcnt vmcnt(16)
	v_mov_b32_e32 v214, v64
	v_mov_b32_e32 v215, v65
	v_mov_b32_e32 v216, v66
	v_mov_b32_e32 v217, v67
	v_lshl_add_u64 v[64:65], v[144:145], 0, s[34:35]
	s_add_i32 s34, 0, 0x1e400
	v_mov_b32_e32 v198, v56
	v_mov_b32_e32 v199, v57
	v_mov_b32_e32 v200, v58
	v_mov_b32_e32 v201, v59
	v_mov_b32_e32 v202, v60
	v_mov_b32_e32 v203, v61
	v_mov_b32_e32 v204, v62
	v_mov_b32_e32 v205, v63
	s_waitcnt vmcnt(15)
	v_mov_b32_e32 v242, v68
	v_mov_b32_e32 v243, v69
	v_mov_b32_e32 v244, v70
	v_mov_b32_e32 v245, v71
	v_add_u32_e32 v116, s34, v143
	ds_read_b128 v[190:193], v116
	v_and_b32_e32 v66, 0xfff, v64
	v_cmp_ne_u32_e64 s[20:21], 0, v66
	v_add_u32_e32 v185, 0, v143
	v_add_u32_e32 v116, 0x1e600, v185
	s_waitcnt lgkmcnt(0)
	v_pk_mul_f32 v[192:193], v[98:99], v[192:193]
	v_pk_mul_f32 v[190:191], v[96:97], v[190:191]
	v_pk_mul_f32 v[98:99], v[102:103], v[192:193]
	v_pk_mul_f32 v[96:97], v[100:101], v[190:191]
	v_cndmask_b32_e64 v56, 0, 1, s[20:21]
	v_cvt_pk_bf16_f32 v100, v96, v97
	v_cvt_pk_bf16_f32 v101, v98, v99
	v_sub_co_u32_e64 v56, s[20:21], v64, v56
	ds_read_b128 v[116:119], v116
	ds_write_b64 v182, v[100:101]
	v_pk_mul_f32 v[100:101], v[104:105], v[190:191]
	v_pk_mul_f32 v[102:103], v[106:107], v[192:193]
	v_subbrev_co_u32_e64 v57, s[20:21], 0, v65, s[20:21]
	v_cvt_pk_bf16_f32 v104, v100, v101
	v_cvt_pk_bf16_f32 v105, v102, v103
	v_cmp_ne_u32_e64 s[20:21], s62, v66
	ds_write_b64 v182, v[104:105] offset:4352
	v_pk_mul_f32 v[104:105], v[108:109], v[190:191]
	v_pk_mul_f32 v[106:107], v[110:111], v[192:193]
	v_cndmask_b32_e64 v66, 0, 1, s[20:21]
	v_mov_b32_e32 v67, s35
	v_cvt_pk_bf16_f32 v108, v104, v105
	v_cvt_pk_bf16_f32 v109, v106, v107
	v_lshlrev_b64 v[68:69], 11, v[64:65]
	v_lshl_add_u64 v[64:65], v[64:65], 0, v[66:67]
	ds_write_b64 v182, v[108:109] offset:8704
	v_pk_mul_f32 v[108:109], v[112:113], v[190:191]
	v_pk_mul_f32 v[110:111], v[114:115], v[192:193]
	v_lshlrev_b64 v[56:57], 11, v[56:57]
	v_lshlrev_b64 v[64:65], 11, v[64:65]
	v_cvt_pk_bf16_f32 v112, v108, v109
	v_cvt_pk_bf16_f32 v113, v110, v111
	v_lshl_add_u64 v[56:57], v[134:135], 0, v[56:57]
	v_lshl_add_u64 v[60:61], v[134:135], 0, v[68:69]
	v_lshl_add_u64 v[64:65], v[134:135], 0, v[64:65]
	v_lshl_add_u64 v[68:69], v[136:137], 0, v[68:69]
	ds_write_b64 v182, v[112:113] offset:13056
	global_load_dwordx4 v[56:59], v[56:57], off
	s_lshl_b32 s48, s48, 6
	global_load_dwordx4 v[60:63], v[60:61], off
	s_nop 0
	global_load_dwordx4 v[64:67], v[64:65], off
	s_nop 0
	global_load_dwordx4 v[68:71], v[68:69], off nt
	s_waitcnt lgkmcnt(0)
	s_barrier
	ds_read_b128 v[218:221], v183
	ds_read_b128 v[230:233], v183 offset:64
	v_and_b32_e32 v250, 0xfff, v184
	v_cmp_ne_u32_e64 s[20:21], 0, v250
	v_add_u32_e32 v184, 4, v184
	s_nop 0
	v_cndmask_b32_e64 v198, 0, v198, s[20:21]
	v_cndmask_b32_e64 v199, 0, v199, s[20:21]
	v_cndmask_b32_e64 v200, 0, v200, s[20:21]
	v_cndmask_b32_e64 v201, 0, v201, s[20:21]
	v_cmp_ne_u32_e64 s[20:21], s62, v250
	v_lshlrev_b32_e32 v246, 16, v202
	v_and_b32_e32 v247, 0xffff0000, v202
	v_cndmask_b32_e64 v214, 0, v214, s[20:21]
	v_cndmask_b32_e64 v215, 0, v215, s[20:21]
	v_cndmask_b32_e64 v216, 0, v216, s[20:21]
	v_cndmask_b32_e64 v217, 0, v217, s[20:21]
	v_pk_mul_f32 v[246:247], v[8:9], v[246:247]
	v_lshlrev_b32_e32 v248, 16, v198
	v_and_b32_e32 v249, 0xffff0000, v198
	v_pk_fma_f32 v[246:247], v[0:1], v[248:249], v[246:247]
	v_lshlrev_b32_e32 v248, 16, v214
	v_and_b32_e32 v249, 0xffff0000, v214
	v_pk_fma_f32 v[246:247], v[16:17], v[248:249], v[246:247]
	v_pk_add_f32 v[246:247], v[24:25], v[246:247]
	v_lshlrev_b32_e32 v248, 16, v242
	v_and_b32_e32 v249, 0xffff0000, v242
	v_pk_mul_f32 v[246:247], v[246:247], v[248:249]
	v_cvt_pk_bf16_f32 v198, v246, v247
	v_lshlrev_b32_e32 v246, 16, v203
	v_and_b32_e32 v247, 0xffff0000, v203
	v_pk_mul_f32 v[246:247], v[10:11], v[246:247]
	v_lshlrev_b32_e32 v248, 16, v199
	v_and_b32_e32 v249, 0xffff0000, v199
	v_pk_fma_f32 v[246:247], v[2:3], v[248:249], v[246:247]
	v_lshlrev_b32_e32 v248, 16, v215
	v_and_b32_e32 v249, 0xffff0000, v215
	v_pk_fma_f32 v[246:247], v[18:19], v[248:249], v[246:247]
	v_pk_add_f32 v[246:247], v[26:27], v[246:247]
	v_lshlrev_b32_e32 v248, 16, v243
	v_and_b32_e32 v249, 0xffff0000, v243
	v_pk_mul_f32 v[246:247], v[246:247], v[248:249]
	v_cvt_pk_bf16_f32 v199, v246, v247
	v_lshlrev_b32_e32 v246, 16, v204
	v_and_b32_e32 v247, 0xffff0000, v204
	v_pk_mul_f32 v[246:247], v[12:13], v[246:247]
	v_lshlrev_b32_e32 v248, 16, v200
	v_and_b32_e32 v249, 0xffff0000, v200
	v_pk_fma_f32 v[246:247], v[4:5], v[248:249], v[246:247]
	v_lshlrev_b32_e32 v248, 16, v216
	v_and_b32_e32 v249, 0xffff0000, v216
	v_pk_fma_f32 v[246:247], v[20:21], v[248:249], v[246:247]
	v_pk_add_f32 v[246:247], v[28:29], v[246:247]
	v_lshlrev_b32_e32 v248, 16, v244
	v_and_b32_e32 v249, 0xffff0000, v244
	v_pk_mul_f32 v[246:247], v[246:247], v[248:249]
	v_cvt_pk_bf16_f32 v200, v246, v247
	v_lshlrev_b32_e32 v246, 16, v205
	v_and_b32_e32 v247, 0xffff0000, v205
	v_pk_mul_f32 v[246:247], v[14:15], v[246:247]
	v_lshlrev_b32_e32 v248, 16, v201
	v_and_b32_e32 v249, 0xffff0000, v201
	v_pk_fma_f32 v[246:247], v[6:7], v[248:249], v[246:247]
	v_lshlrev_b32_e32 v248, 16, v217
	v_and_b32_e32 v249, 0xffff0000, v217
	v_pk_fma_f32 v[246:247], v[22:23], v[248:249], v[246:247]
	v_pk_add_f32 v[246:247], v[30:31], v[246:247]
	v_lshlrev_b32_e32 v248, 16, v245
	v_and_b32_e32 v249, 0xffff0000, v245
	v_pk_mul_f32 v[246:247], v[246:247], v[248:249]
	v_cvt_pk_bf16_f32 v201, v246, v247
	global_store_dwordx4 v[152:153], v[198:201], off
	s_nop 1
	ds_read_b128 v[242:245], v183 offset:128
	s_waitcnt lgkmcnt(2)
	v_mfma_f32_16x16x32_bf16 v[198:201], v[218:221], v[122:125], 0
	v_mfma_f32_16x16x32_bf16 v[202:205], v[218:221], v[126:129], 0
	ds_read_b128 v[218:221], v183 offset:192
	s_waitcnt lgkmcnt(2)
	v_mfma_f32_16x16x32_bf16 v[198:201], v[230:233], v[130:133], v[198:201]
	v_mfma_f32_16x16x32_bf16 v[202:205], v[230:233], v[160:163], v[202:205]
	ds_read_b128 v[230:233], v170 offset:61440
	ds_read_b128 v[122:125], v171 offset:44032
	ds_read_b128 v[126:129], v172 offset:44032
	s_waitcnt lgkmcnt(4)
	v_mfma_f32_16x16x32_bf16 v[198:201], v[242:245], v[210:213], v[198:201]
	v_mfma_f32_16x16x32_bf16 v[202:205], v[242:245], v[154:157], v[202:205]
	ds_read_b128 v[242:245], v170 offset:61504
	ds_read_b128 v[130:133], v171 offset:44096
	ds_read_b128 v[160:163], v172 offset:44096
	s_waitcnt lgkmcnt(6)
	v_mfma_f32_16x16x32_bf16 v[198:201], v[218:221], v[206:209], v[198:201]
	v_mfma_f32_16x16x32_bf16 v[202:205], v[218:221], v[174:177], v[202:205]
	ds_read_b128 v[218:221], v170 offset:61568
	ds_read_b128 v[210:213], v171 offset:44160
	ds_read_b128 v[154:157], v172 offset:44160
	s_waitcnt lgkmcnt(6)
	v_mfma_f32_16x16x32_bf16 v[190:193], v[230:233], v[122:125], 0
	v_mfma_f32_16x16x32_bf16 v[194:197], v[230:233], v[126:129], 0
	ds_read_b128 v[230:233], v170 offset:61632
	ds_read_b128 v[206:209], v171 offset:44224
	ds_read_b128 v[174:177], v172 offset:44224
	s_waitcnt lgkmcnt(6)
	v_mfma_f32_16x16x32_bf16 v[190:193], v[242:245], v[130:133], v[190:193]
	v_mfma_f32_16x16x32_bf16 v[194:197], v[242:245], v[160:163], v[194:197]
	ds_read_b64_tr_b16 v[242:243], v139
	ds_read_b64_tr_b16 v[244:245], v139 offset:512
	ds_read_b128 v[246:249], v142
	ds_read_b128 v[250:253], v159
	s_waitcnt lgkmcnt(7)
	v_mfma_f32_16x16x32_bf16 v[190:193], v[218:221], v[210:213], v[190:193]
	v_mfma_f32_16x16x32_bf16 v[194:197], v[218:221], v[154:157], v[194:197]
	ds_read_b64_tr_b16 v[218:219], v139 offset:4096
	ds_read_b64_tr_b16 v[220:221], v139 offset:4608
	ds_read_b128 v[222:225], v142 offset:64
	ds_read_b128 v[226:229], v159 offset:64
	s_waitcnt lgkmcnt(8)
	v_mfma_f32_16x16x32_bf16 v[190:193], v[230:233], v[206:209], v[190:193]
	v_mfma_f32_16x16x32_bf16 v[194:197], v[230:233], v[174:177], v[194:197]
	s_nop 6
	v_cndmask_b32_e32 v190, 0, v190, vcc
	v_cndmask_b32_e64 v191, 0, v191, s[6:7]
	v_cndmask_b32_e64 v192, 0, v192, s[8:9]
	v_cndmask_b32_e64 v193, 0, v193, s[10:11]
	v_cvt_pk_bf16_f32 v190, v190, v191
	v_cvt_pk_bf16_f32 v191, v192, v193
	v_cndmask_b32_e64 v194, 0, v194, s[12:13]
	v_cndmask_b32_e64 v195, 0, v195, s[14:15]
	v_cndmask_b32_e64 v196, 0, v196, s[16:17]
	v_cndmask_b32_e64 v197, 0, v197, s[18:19]
	v_cvt_pk_bf16_f32 v194, v194, v195
	v_cvt_pk_bf16_f32 v195, v196, v197
	ds_write_b64 v164, v[190:191] offset:9216
	ds_write_b64 v180, v[194:195] offset:9216
	ds_read_b64_tr_b16 v[190:191], v178 offset:17408
	ds_read_b64_tr_b16 v[192:193], v178 offset:18496
	ds_read_b64_tr_b16 v[194:195], v178 offset:26112
	ds_read_b64_tr_b16 v[196:197], v178 offset:27200
	s_waitcnt lgkmcnt(10)
	v_mfma_f32_16x16x32_bf16 v[198:201], v[242:245], v[246:249], v[198:201]
	v_mfma_f32_16x16x32_bf16 v[202:205], v[242:245], v[250:253], v[202:205]
	ds_read_b64_tr_b16 v[242:243], v186
	ds_read_b64_tr_b16 v[244:245], v186 offset:512
	ds_read_b64_tr_b16 v[246:247], v187
	ds_read_b64_tr_b16 v[248:249], v187 offset:512
	s_waitcnt lgkmcnt(10)
	v_mfma_f32_16x16x32_bf16 v[198:201], v[218:221], v[222:225], v[198:201]
	v_mfma_f32_16x16x32_bf16 v[202:205], v[218:221], v[226:229], v[202:205]
	ds_read_b64_tr_b16 v[218:219], v188
	ds_read_b64_tr_b16 v[220:221], v188 offset:512
	ds_read_b64_tr_b16 v[222:223], v189
	ds_read_b64_tr_b16 v[224:225], v189 offset:512
	s_waitcnt lgkmcnt(8)
	ds_read_b64_tr_b16 v[230:231], v186 offset:4096
	ds_read_b64_tr_b16 v[232:233], v186 offset:4608
	ds_read_b64_tr_b16 v[234:235], v187 offset:4096
	ds_read_b64_tr_b16 v[236:237], v187 offset:4608
	s_waitcnt lgkmcnt(8)
	v_mfma_f32_16x16x32_bf16 v[96:99], v[190:193], v[242:245], v[96:99]
	v_mfma_f32_16x16x32_bf16 v[100:103], v[190:193], v[246:249], v[100:103]
	ds_read_b64_tr_b16 v[242:243], v188 offset:4096
	ds_read_b64_tr_b16 v[244:245], v188 offset:4608
	ds_read_b64_tr_b16 v[246:247], v189 offset:4096
	ds_read_b64_tr_b16 v[248:249], v189 offset:4608
	v_cvt_pk_bf16_f32 v198, v198, v199
	v_cvt_pk_bf16_f32 v199, v200, v201
	v_cvt_pk_bf16_f32 v200, v202, v203
	v_cvt_pk_bf16_f32 v201, v204, v205
	v_add_u32_e32 v254, s48, v173
	v_mad_u64_u32 v[254:255], s[20:21], v254, s42, 0
	v_lshl_add_u64 v[254:255], v[254:255], 1, v[150:151]
	v_permlane16_swap_b32_e32 v198, v200
	v_permlane16_swap_b32_e32 v199, v201
	global_store_dwordx4 v[254:255], v[198:201], off
	s_waitcnt lgkmcnt(8)
	v_mfma_f32_16x16x32_bf16 v[104:107], v[190:193], v[218:221], v[104:107]
	v_mfma_f32_16x16x32_bf16 v[214:217], v[190:193], v[222:225], v[108:111]
	s_waitcnt lgkmcnt(4)
	v_mfma_f32_16x16x32_bf16 v[112:115], v[194:197], v[230:233], v[96:99]
	v_mfma_f32_16x16x32_bf16 v[108:111], v[194:197], v[234:237], v[100:103]
	s_waitcnt lgkmcnt(0)
	v_mfma_f32_16x16x32_bf16 v[104:107], v[194:197], v[242:245], v[104:107]
	v_mfma_f32_16x16x32_bf16 v[100:103], v[194:197], v[246:249], v[214:217]
	s_min_u32 s20, s44, 59
	s_waitcnt lgkmcnt(0)
	s_barrier
	s_waitcnt vmcnt(18)
	ds_write_b128 v168, v[72:75]
	s_waitcnt vmcnt(17)
	ds_write_b128 v168, v[80:83] offset:8704
	s_waitcnt vmcnt(15)
	ds_write_b128 v168, v[76:79] offset:17408
	s_waitcnt vmcnt(14)
	ds_write_b128 v168, v[84:87] offset:26112
	s_waitcnt vmcnt(16)
	ds_write_b128 v169, v[88:91] offset:34816
	v_add_u32_e32 v72, s34, v138
	s_add_i32 s34, s20, 4
	s_waitcnt vmcnt(13)
	s_cmp_lg_u32 s69, 0
	s_cbranch_scc1 .Lev_skip_b
	ds_write_b128 v72, v[92:95]
.Lev_skip_b:
	v_sub_u32_e64 v72, 59, s44 clamp
	s_and_b64 s[20:21], exec, s[38:39]
	v_readfirstlane_b32 s20, v72
	s_cselect_b32 s48, s34, s20
	v_add_u32_e32 v96, s61, v143
	s_lshl_b32 s34, s48, 13
	s_lshl_b32 s49, s48, 14
	ds_read_b128 v[222:225], v96
	s_add_u32 s20, s43, s49
	s_addc_u32 s21, s63, 0
	v_lshl_add_u64 v[76:77], s[20:21], 0, v[120:121]
	global_load_dwordx4 v[72:75], v120, s[20:21] nt
	v_add_co_u32_e64 v76, s[20:21], s60, v76
	s_waitcnt lgkmcnt(0)
	v_pk_mul_f32 v[118:119], v[118:119], v[224:225]
	v_addc_co_u32_e64 v77, s[20:21], 0, v77, s[20:21]
	v_pk_mul_f32 v[116:117], v[116:117], v[222:223]
	s_add_u32 s20, s64, s49
	v_pk_mul_f32 v[114:115], v[114:115], v[118:119]
	v_pk_mul_f32 v[112:113], v[112:113], v[116:117]
	s_addc_u32 s21, s65, 0
	v_add_u32_e32 v96, 0x1ea00, v185
	v_cvt_pk_bf16_f32 v222, v112, v113
	v_cvt_pk_bf16_f32 v223, v114, v115
	v_pk_mul_f32 v[110:111], v[110:111], v[118:119]
	v_pk_mul_f32 v[108:109], v[108:109], v[116:117]
	v_lshl_add_u64 v[84:85], s[20:21], 0, v[120:121]
	ds_read_b128 v[96:99], v96
	ds_write_b64 v182, v[222:223]
	v_cvt_pk_bf16_f32 v222, v108, v109
	v_cvt_pk_bf16_f32 v223, v110, v111
	v_pk_mul_f32 v[106:107], v[106:107], v[118:119]
	v_pk_mul_f32 v[104:105], v[104:105], v[116:117]
	v_pk_mul_f32 v[102:103], v[102:103], v[118:119]
	v_pk_mul_f32 v[100:101], v[100:101], v[116:117]
	global_load_dwordx4 v[80:83], v[76:77], off nt
	v_lshl_add_u64 v[88:89], v[146:147], 0, s[34:35]
	global_load_dwordx4 v[88:91], v[88:89], off nt
	global_load_dwordx4 v[76:79], v120, s[20:21] nt
	v_add_co_u32_e64 v84, s[20:21], s60, v84
	s_lshl_b32 s34, s48, 10
	ds_write_b64 v182, v[222:223] offset:4352
	v_cvt_pk_bf16_f32 v222, v104, v105
	v_cvt_pk_bf16_f32 v223, v106, v107
	v_cvt_pk_bf16_f32 v116, v100, v101
	v_cvt_pk_bf16_f32 v117, v102, v103
	v_addc_co_u32_e64 v85, s[20:21], 0, v85, s[20:21]
	global_load_dwordx4 v[84:87], v[84:85], off nt
	v_lshl_add_u64 v[92:93], v[148:149], 0, s[34:35]
	global_load_dwordx4 v[92:95], v[92:93], off
	ds_write_b64 v182, v[222:223] offset:8704
	ds_write_b64 v182, v[116:117] offset:13056
	s_waitcnt lgkmcnt(0)
	s_barrier
	ds_read_b128 v[218:221], v183
	ds_read_b128 v[230:233], v183 offset:64
	ds_read_b128 v[242:245], v183 offset:128
	s_add_i32 s34, s44, 1
	s_and_b64 s[20:21], exec, s[38:39]
	s_cselect_b32 s20, s34, s47
	s_lshl_b32 s34, s20, 6
	s_add_i32 s47, s47, -2
	v_lshl_add_u64 v[152:153], v[152:153], 0, s[36:37]
	s_waitcnt lgkmcnt(2)
	v_mfma_f32_16x16x32_bf16 v[198:201], v[218:221], v[122:125], 0
	v_mfma_f32_16x16x32_bf16 v[202:205], v[218:221], v[126:129], 0
	ds_read_b128 v[218:221], v183 offset:192
	s_waitcnt lgkmcnt(2)
	v_mfma_f32_16x16x32_bf16 v[198:201], v[230:233], v[130:133], v[198:201]
	v_mfma_f32_16x16x32_bf16 v[202:205], v[230:233], v[160:163], v[202:205]
	ds_read_b128 v[230:233], v170 offset:17408
	ds_read_b128 v[122:125], v171
	ds_read_b128 v[126:129], v172
	s_waitcnt lgkmcnt(4)
	v_mfma_f32_16x16x32_bf16 v[198:201], v[242:245], v[210:213], v[198:201]
	v_mfma_f32_16x16x32_bf16 v[202:205], v[242:245], v[154:157], v[202:205]
	ds_read_b128 v[242:245], v170 offset:17472
	ds_read_b128 v[130:133], v171 offset:64
	ds_read_b128 v[160:163], v172 offset:64
	s_waitcnt lgkmcnt(6)
	v_mfma_f32_16x16x32_bf16 v[198:201], v[218:221], v[206:209], v[198:201]
	v_mfma_f32_16x16x32_bf16 v[202:205], v[218:221], v[174:177], v[202:205]
	ds_read_b128 v[218:221], v170 offset:17536
	ds_read_b128 v[210:213], v171 offset:128
	ds_read_b128 v[154:157], v172 offset:128
	s_waitcnt lgkmcnt(6)
	v_mfma_f32_16x16x32_bf16 v[190:193], v[230:233], v[122:125], 0
	v_mfma_f32_16x16x32_bf16 v[194:197], v[230:233], v[126:129], 0
	ds_read_b128 v[230:233], v170 offset:17600
	ds_read_b128 v[206:209], v171 offset:192
	ds_read_b128 v[174:177], v172 offset:192
	s_waitcnt lgkmcnt(6)
	v_mfma_f32_16x16x32_bf16 v[190:193], v[242:245], v[130:133], v[190:193]
	v_mfma_f32_16x16x32_bf16 v[194:197], v[242:245], v[160:163], v[194:197]
	ds_read_b64_tr_b16 v[242:243], v139 offset:44032
	ds_read_b64_tr_b16 v[244:245], v139 offset:44544
	ds_read_b128 v[246:249], v142 offset:9216
	ds_read_b128 v[250:253], v159 offset:9216
	s_waitcnt lgkmcnt(7)
	v_mfma_f32_16x16x32_bf16 v[190:193], v[218:221], v[210:213], v[190:193]
	v_mfma_f32_16x16x32_bf16 v[194:197], v[218:221], v[154:157], v[194:197]
	ds_read_b64_tr_b16 v[218:219], v139 offset:48128
	ds_read_b64_tr_b16 v[220:221], v139 offset:48640
	ds_read_b128 v[222:225], v142 offset:9280
	ds_read_b128 v[226:229], v159 offset:9280
	s_waitcnt lgkmcnt(8)
	v_mfma_f32_16x16x32_bf16 v[190:193], v[230:233], v[206:209], v[190:193]
	v_mfma_f32_16x16x32_bf16 v[194:197], v[230:233], v[174:177], v[194:197]
	s_nop 6
	v_cndmask_b32_e32 v190, 0, v190, vcc
	v_cndmask_b32_e64 v191, 0, v191, s[6:7]
	v_cndmask_b32_e64 v192, 0, v192, s[8:9]
	v_cndmask_b32_e64 v193, 0, v193, s[10:11]
	v_cvt_pk_bf16_f32 v190, v190, v191
	v_cvt_pk_bf16_f32 v191, v192, v193
	v_cndmask_b32_e64 v194, 0, v194, s[12:13]
	v_cndmask_b32_e64 v195, 0, v195, s[14:15]
	v_cndmask_b32_e64 v196, 0, v196, s[16:17]
	v_cndmask_b32_e64 v197, 0, v197, s[18:19]
	v_cvt_pk_bf16_f32 v194, v194, v195
	v_cvt_pk_bf16_f32 v195, v196, v197
	ds_write_b64 v164, v[190:191]
	ds_write_b64 v180, v[194:195]
	ds_read_b64_tr_b16 v[190:191], v178 offset:61440
	ds_read_b64_tr_b16 v[192:193], v178 offset:62528
	ds_read_b64_tr_b16 v[194:195], v181 offset:8704
	ds_read_b64_tr_b16 v[196:197], v181 offset:9792
	s_waitcnt lgkmcnt(10)
	v_mfma_f32_16x16x32_bf16 v[198:201], v[242:245], v[246:249], v[198:201]
	v_mfma_f32_16x16x32_bf16 v[202:205], v[242:245], v[250:253], v[202:205]
	ds_read_b64_tr_b16 v[242:243], v186 offset:44032
	ds_read_b64_tr_b16 v[244:245], v186 offset:44544
	ds_read_b64_tr_b16 v[246:247], v187 offset:44032
	ds_read_b64_tr_b16 v[248:249], v187 offset:44544
	s_waitcnt lgkmcnt(10)
	v_mfma_f32_16x16x32_bf16 v[198:201], v[218:221], v[222:225], v[198:201]
	v_mfma_f32_16x16x32_bf16 v[202:205], v[218:221], v[226:229], v[202:205]
	ds_read_b64_tr_b16 v[218:219], v188 offset:44032
	ds_read_b64_tr_b16 v[220:221], v188 offset:44544
	ds_read_b64_tr_b16 v[222:223], v189 offset:44032
	ds_read_b64_tr_b16 v[224:225], v189 offset:44544
	s_waitcnt lgkmcnt(8)
	ds_read_b64_tr_b16 v[230:231], v186 offset:48128
	ds_read_b64_tr_b16 v[232:233], v186 offset:48640
	ds_read_b64_tr_b16 v[234:235], v187 offset:48128
	ds_read_b64_tr_b16 v[236:237], v187 offset:48640
	s_waitcnt lgkmcnt(8)
	v_mfma_f32_16x16x32_bf16 v[112:115], v[190:193], v[242:245], v[112:115]
	v_mfma_f32_16x16x32_bf16 v[108:111], v[190:193], v[246:249], v[108:111]
	ds_read_b64_tr_b16 v[242:243], v188 offset:48128
	ds_read_b64_tr_b16 v[244:245], v188 offset:48640
	ds_read_b64_tr_b16 v[246:247], v189 offset:48128
	ds_read_b64_tr_b16 v[248:249], v189 offset:48640
	v_cvt_pk_bf16_f32 v198, v198, v199
	v_cvt_pk_bf16_f32 v199, v200, v201
	v_cvt_pk_bf16_f32 v200, v202, v203
	v_cvt_pk_bf16_f32 v201, v204, v205
	v_add_u32_e32 v254, s34, v173
	v_mad_u64_u32 v[254:255], s[20:21], v254, s42, 0
	v_lshl_add_u64 v[254:255], v[254:255], 1, v[150:151]
	v_permlane16_swap_b32_e32 v198, v200
	v_permlane16_swap_b32_e32 v199, v201
	global_store_dwordx4 v[254:255], v[198:201], off
	s_waitcnt lgkmcnt(8)
	v_mfma_f32_16x16x32_bf16 v[214:217], v[190:193], v[218:221], v[104:107]
	v_mfma_f32_16x16x32_bf16 v[116:119], v[190:193], v[222:225], v[100:103]
	s_waitcnt lgkmcnt(4)
	v_mfma_f32_16x16x32_bf16 v[100:103], v[194:197], v[230:233], v[112:115]
	v_mfma_f32_16x16x32_bf16 v[104:107], v[194:197], v[234:237], v[108:111]
	s_waitcnt lgkmcnt(0)
	v_mfma_f32_16x16x32_bf16 v[108:111], v[194:197], v[242:245], v[214:217]
	v_mfma_f32_16x16x32_bf16 v[112:115], v[194:197], v[246:249], v[116:119]
	s_add_i32 s20, s44, 2
	s_cmp_lt_u32 s44, 62
	s_mov_b32 s44, s20
	s_waitcnt lgkmcnt(0)
	s_barrier
	s_cbranch_scc1 .LBB0_350
	s_add_i32 s30, s30, s28
	v_lshl_add_u64 v[140:141], v[140:141], 0, s[26:27]
	s_cmpk_lt_i32 s30, 0x100
	v_add_u32_e32 v165, s29, v165
	s_cbranch_scc1 .LBB0_344
